# code placement: the eight GEMM K-loop heads aligned to 64 bytes (on top of the combined version)
# baseline (speedup 1.0000x reference)
;     ...
;   f32x16 acc[4][2];
; #pragma unroll
;   for (int a = 0; a < 4; ++a)
; #pragma unroll
;     for (int b = 0; b < 2; ++b)
; #pragma unroll
;       for (int i = 0; i < 16; ++i) acc[a][b][i] = 0.f;
;   const bool vt = epi.vtype(n0 + wn * 64);
;   int st_last = 0;
;   if (pm == 2) K >>= 1;
;   if (DEEP) {
;     const bf16_t* AgN = tmN >= 0 ? A + (size_t)(tmN << 8) * lda : nullptr;
;     const bf16_t* BgN = Bt + (size_t)(tnN << 7) * ldb;
;     if (vt) st_last = gemm_kloop<true>(Ag, lda, Bg, ldb, K >> 5, sA, acc, tid, wm, wn, r, h, st0, pre, AgN, BgN);
;     else st_last = gemm_kloop<false>(Ag, lda, Bg, ldb, K >> 5, sA, acc, tid, wm, wn, r, h, st0, pre, AgN, BgN);
.LBB0_199:
	v_lshlrev_b64 v[138:139], 1, v[32:33]
	s_add_u32 s24, s34, s41
	v_lshlrev_b32_e32 v166, 10, v0
	v_lshlrev_b32_e32 v165, 10, v1
	v_lshl_add_u64 v[0:1], v[132:133], 1, v[138:139]
	s_addc_u32 s25, s35, s42
	v_lshl_add_u64 v[2:3], v[130:131], 1, v[138:139]
	v_lshl_add_u64 v[140:141], s[24:25], 0, v[0:1]
	v_lshl_add_u64 v[142:143], s[24:25], 0, v[2:3]
	s_add_i32 s24, s39, s43
	s_lshl_b32 s24, s24, 11
	s_or_b32 s44, s24, s40
	v_lshlrev_b64 v[4:5], 1, v[136:137]
	v_mad_i64_i32 v[4:5], s[24:25], s44, v211, v[4:5]
	v_lshl_add_u64 v[4:5], v[4:5], 0, v[138:139]
	v_lshl_add_u64 v[144:145], s[6:7], 0, v[4:5]
	v_lshlrev_b64 v[4:5], 1, v[134:135]
	v_mad_i64_i32 v[0:1], s[24:25], s44, v211, v[0:1]
	v_mad_i64_i32 v[4:5], s[24:25], s44, v211, v[4:5]
	v_lshl_add_u64 v[148:149], s[6:7], 0, v[0:1]
	v_mad_i64_i32 v[0:1], s[24:25], s44, v211, v[2:3]
	v_lshl_add_u64 v[4:5], v[4:5], 0, v[138:139]
	v_lshl_add_u64 v[150:151], s[6:7], 0, v[0:1]
	v_mov_b32_e32 v0, 0
	v_lshl_add_u64 v[146:147], s[6:7], 0, v[4:5]
	s_mov_b64 s[24:25], 0
	v_mov_b32_e32 v1, v0
	v_mov_b32_e32 v2, v0
	v_mov_b32_e32 v3, v0
	v_mov_b32_e32 v4, v0
	v_mov_b32_e32 v5, v0
	v_mov_b32_e32 v6, v0
	v_mov_b32_e32 v7, v0
	v_mov_b32_e32 v8, v0
	v_mov_b32_e32 v9, v0
	v_mov_b32_e32 v10, v0
	v_mov_b32_e32 v11, v0
	v_mov_b32_e32 v12, v0
	v_mov_b32_e32 v13, v0
	v_mov_b32_e32 v14, v0
	v_mov_b32_e32 v15, v0
	v_mov_b32_e32 v16, v0
	v_mov_b32_e32 v17, v0
	v_mov_b32_e32 v18, v0
	v_mov_b32_e32 v19, v0
	v_mov_b32_e32 v20, v0
	v_mov_b32_e32 v21, v0
	v_mov_b32_e32 v22, v0
	v_mov_b32_e32 v23, v0
	v_mov_b32_e32 v24, v0
	v_mov_b32_e32 v25, v0
	v_mov_b32_e32 v26, v0
	v_mov_b32_e32 v27, v0
	v_mov_b32_e32 v28, v0
	v_mov_b32_e32 v29, v0
	v_mov_b32_e32 v30, v0
	v_mov_b32_e32 v31, v0
	v_mov_b32_e32 v34, v0
	v_mov_b32_e32 v35, v0
	v_mov_b32_e32 v36, v0
	v_mov_b32_e32 v37, v0
	v_mov_b32_e32 v38, v0
	v_mov_b32_e32 v39, v0
	v_mov_b32_e32 v40, v0
	v_mov_b32_e32 v41, v0
	v_mov_b32_e32 v42, v0
	v_mov_b32_e32 v43, v0
	v_mov_b32_e32 v44, v0
	v_mov_b32_e32 v45, v0
	v_mov_b32_e32 v46, v0
	v_mov_b32_e32 v47, v0
	v_mov_b32_e32 v48, v0
	v_mov_b32_e32 v49, v0
	v_mov_b32_e32 v50, v0
	v_mov_b32_e32 v51, v0
	v_mov_b32_e32 v52, v0
	v_mov_b32_e32 v53, v0
	v_mov_b32_e32 v54, v0
	v_mov_b32_e32 v55, v0
	v_mov_b32_e32 v56, v0
	v_mov_b32_e32 v57, v0
	v_mov_b32_e32 v58, v0
	v_mov_b32_e32 v59, v0
	v_mov_b32_e32 v60, v0
	v_mov_b32_e32 v61, v0
	v_mov_b32_e32 v62, v0
	v_mov_b32_e32 v63, v0
	v_mov_b32_e32 v64, v0
	v_mov_b32_e32 v65, v0
	v_mov_b32_e32 v66, v0
	v_mov_b32_e32 v67, v0
	v_mov_b32_e32 v68, v0
	v_mov_b32_e32 v69, v0
	v_mov_b32_e32 v70, v0
	v_mov_b32_e32 v71, v0
	v_mov_b32_e32 v72, v0
	v_mov_b32_e32 v73, v0
	v_mov_b32_e32 v74, v0
	v_mov_b32_e32 v75, v0
	v_mov_b32_e32 v76, v0
	v_mov_b32_e32 v77, v0
	v_mov_b32_e32 v78, v0
	v_mov_b32_e32 v79, v0
	v_mov_b32_e32 v80, v0
	v_mov_b32_e32 v81, v0
	v_mov_b32_e32 v82, v0
	v_mov_b32_e32 v83, v0
	v_mov_b32_e32 v84, v0
	v_mov_b32_e32 v85, v0
	v_mov_b32_e32 v86, v0
	v_mov_b32_e32 v87, v0
	v_mov_b32_e32 v88, v0
	v_mov_b32_e32 v89, v0
	v_mov_b32_e32 v90, v0
	v_mov_b32_e32 v91, v0
	v_mov_b32_e32 v92, v0
	v_mov_b32_e32 v93, v0
	v_mov_b32_e32 v94, v0
	v_mov_b32_e32 v95, v0
	v_mov_b32_e32 v96, v0
	v_mov_b32_e32 v97, v0
	v_mov_b32_e32 v98, v0
	v_mov_b32_e32 v99, v0
	v_mov_b32_e32 v100, v0
	v_mov_b32_e32 v101, v0
	v_mov_b32_e32 v102, v0
	v_mov_b32_e32 v103, v0
	v_mov_b32_e32 v104, v0
	v_mov_b32_e32 v105, v0
	v_mov_b32_e32 v106, v0
	v_mov_b32_e32 v107, v0
	v_mov_b32_e32 v108, v0
	v_mov_b32_e32 v109, v0
	v_mov_b32_e32 v110, v0
	v_mov_b32_e32 v111, v0
	v_mov_b32_e32 v112, v0
	v_mov_b32_e32 v113, v0
	v_mov_b32_e32 v114, v0
	v_mov_b32_e32 v115, v0
	v_mov_b32_e32 v116, v0
	v_mov_b32_e32 v117, v0
	v_mov_b32_e32 v118, v0
	v_mov_b32_e32 v119, v0
	v_mov_b32_e32 v120, v0
	v_mov_b32_e32 v121, v0
	v_mov_b32_e32 v122, v0
	v_mov_b32_e32 v123, v0
	v_mov_b32_e32 v124, v0
	v_mov_b32_e32 v125, v0
	v_mov_b32_e32 v126, v0
	v_mov_b32_e32 v127, v0
	v_mov_b32_e32 v128, v0
	v_mov_b32_e32 v129, v0
	v_readfirstlane_b32 s99, v163
	s_lshl_b32 s99, s99, 1
	.p2align 6

;     ...
;   f32x16 acc[4][2];
; #pragma unroll
;   for (int a = 0; a < 4; ++a)
; #pragma unroll
;     for (int b = 0; b < 2; ++b)
; #pragma unroll
;       for (int i = 0; i < 16; ++i) acc[a][b][i] = 0.f;
;   const bool vt = epi.vtype(n0 + wn * 64);
;   int st_last = 0;
;   if (pm == 2) K >>= 1;
;   if (DEEP) {
;     const bf16_t* AgN = tmN >= 0 ? A + (size_t)(tmN << 8) * lda : nullptr;
;     const bf16_t* BgN = Bt + (size_t)(tnN << 7) * ldb;
;     if (vt) st_last = gemm_kloop<true>(Ag, lda, Bg, ldb, K >> 5, sA, acc, tid, wm, wn, r, h, st0, pre, AgN, BgN);
;     else st_last = gemm_kloop<false>(Ag, lda, Bg, ldb, K >> 5, sA, acc, tid, wm, wn, r, h, st0, pre, AgN, BgN);
.LBB0_209:
	v_lshlrev_b64 v[138:139], 1, v[32:33]
	s_add_u32 s16, s34, s41
	v_lshl_add_u64 v[0:1], v[132:133], 1, v[138:139]
	s_addc_u32 s17, s35, s42
	v_lshl_add_u64 v[2:3], v[130:131], 1, v[138:139]
	s_add_i32 s39, s39, s43
	v_lshl_add_u64 v[140:141], s[16:17], 0, v[0:1]
	v_lshl_add_u64 v[142:143], s[16:17], 0, v[2:3]
	s_lshl_b32 s16, s39, 11
	s_or_b32 s18, s16, s40
	v_lshlrev_b64 v[4:5], 1, v[136:137]
	v_mad_i64_i32 v[4:5], s[16:17], s18, v211, v[4:5]
	v_lshl_add_u64 v[4:5], v[4:5], 0, v[138:139]
	v_lshl_add_u64 v[144:145], s[6:7], 0, v[4:5]
	v_lshlrev_b64 v[4:5], 1, v[134:135]
	v_mad_i64_i32 v[0:1], s[16:17], s18, v211, v[0:1]
	v_mad_i64_i32 v[4:5], s[16:17], s18, v211, v[4:5]
	v_lshl_add_u64 v[148:149], s[6:7], 0, v[0:1]
	v_mad_i64_i32 v[0:1], s[16:17], s18, v211, v[2:3]
	v_lshl_add_u64 v[4:5], v[4:5], 0, v[138:139]
	v_lshl_add_u64 v[150:151], s[6:7], 0, v[0:1]
	v_mov_b32_e32 v0, 0
	v_lshlrev_b32_e32 v166, 10, v6
	v_lshlrev_b32_e32 v165, 10, v7
	v_lshl_add_u64 v[146:147], s[6:7], 0, v[4:5]
	s_mov_b64 s[16:17], 0
	v_mov_b32_e32 v1, v0
	v_mov_b32_e32 v2, v0
	v_mov_b32_e32 v3, v0
	v_mov_b32_e32 v4, v0
	v_mov_b32_e32 v5, v0
	v_mov_b32_e32 v6, v0
	v_mov_b32_e32 v7, v0
	v_mov_b32_e32 v8, v0
	v_mov_b32_e32 v9, v0
	v_mov_b32_e32 v10, v0
	v_mov_b32_e32 v11, v0
	v_mov_b32_e32 v12, v0
	v_mov_b32_e32 v13, v0
	v_mov_b32_e32 v14, v0
	v_mov_b32_e32 v15, v0
	v_mov_b32_e32 v16, v0
	v_mov_b32_e32 v17, v0
	v_mov_b32_e32 v18, v0
	v_mov_b32_e32 v19, v0
	v_mov_b32_e32 v20, v0
	v_mov_b32_e32 v21, v0
	v_mov_b32_e32 v22, v0
	v_mov_b32_e32 v23, v0
	v_mov_b32_e32 v24, v0
	v_mov_b32_e32 v25, v0
	v_mov_b32_e32 v26, v0
	v_mov_b32_e32 v27, v0
	v_mov_b32_e32 v28, v0
	v_mov_b32_e32 v29, v0
	v_mov_b32_e32 v30, v0
	v_mov_b32_e32 v31, v0
	v_mov_b32_e32 v34, v0
	v_mov_b32_e32 v35, v0
	v_mov_b32_e32 v36, v0
	v_mov_b32_e32 v37, v0
	v_mov_b32_e32 v38, v0
	v_mov_b32_e32 v39, v0
	v_mov_b32_e32 v40, v0
	v_mov_b32_e32 v41, v0
	v_mov_b32_e32 v42, v0
	v_mov_b32_e32 v43, v0
	v_mov_b32_e32 v44, v0
	v_mov_b32_e32 v45, v0
	v_mov_b32_e32 v46, v0
	v_mov_b32_e32 v47, v0
	v_mov_b32_e32 v48, v0
	v_mov_b32_e32 v49, v0
	v_mov_b32_e32 v50, v0
	v_mov_b32_e32 v51, v0
	v_mov_b32_e32 v52, v0
	v_mov_b32_e32 v53, v0
	v_mov_b32_e32 v54, v0
	v_mov_b32_e32 v55, v0
	v_mov_b32_e32 v56, v0
	v_mov_b32_e32 v57, v0
	v_mov_b32_e32 v58, v0
	v_mov_b32_e32 v59, v0
	v_mov_b32_e32 v60, v0
	v_mov_b32_e32 v61, v0
	v_mov_b32_e32 v62, v0
	v_mov_b32_e32 v63, v0
	v_mov_b32_e32 v64, v0
	v_mov_b32_e32 v65, v0
	v_mov_b32_e32 v66, v0
	v_mov_b32_e32 v67, v0
	v_mov_b32_e32 v68, v0
	v_mov_b32_e32 v69, v0
	v_mov_b32_e32 v70, v0
	v_mov_b32_e32 v71, v0
	v_mov_b32_e32 v72, v0
	v_mov_b32_e32 v73, v0
	v_mov_b32_e32 v74, v0
	v_mov_b32_e32 v75, v0
	v_mov_b32_e32 v76, v0
	v_mov_b32_e32 v77, v0
	v_mov_b32_e32 v78, v0
	v_mov_b32_e32 v79, v0
	v_mov_b32_e32 v80, v0
	v_mov_b32_e32 v81, v0
	v_mov_b32_e32 v82, v0
	v_mov_b32_e32 v83, v0
	v_mov_b32_e32 v84, v0
	v_mov_b32_e32 v85, v0
	v_mov_b32_e32 v86, v0
	v_mov_b32_e32 v87, v0
	v_mov_b32_e32 v88, v0
	v_mov_b32_e32 v89, v0
	v_mov_b32_e32 v90, v0
	v_mov_b32_e32 v91, v0
	v_mov_b32_e32 v92, v0
	v_mov_b32_e32 v93, v0
	v_mov_b32_e32 v94, v0
	v_mov_b32_e32 v95, v0
	v_mov_b32_e32 v96, v0
	v_mov_b32_e32 v97, v0
	v_mov_b32_e32 v98, v0
	v_mov_b32_e32 v99, v0
	v_mov_b32_e32 v100, v0
	v_mov_b32_e32 v101, v0
	v_mov_b32_e32 v102, v0
	v_mov_b32_e32 v103, v0
	v_mov_b32_e32 v104, v0
	v_mov_b32_e32 v105, v0
	v_mov_b32_e32 v106, v0
	v_mov_b32_e32 v107, v0
	v_mov_b32_e32 v108, v0
	v_mov_b32_e32 v109, v0
	v_mov_b32_e32 v110, v0
	v_mov_b32_e32 v111, v0
	v_mov_b32_e32 v112, v0
	v_mov_b32_e32 v113, v0
	v_mov_b32_e32 v114, v0
	v_mov_b32_e32 v115, v0
	v_mov_b32_e32 v116, v0
	v_mov_b32_e32 v117, v0
	v_mov_b32_e32 v118, v0
	v_mov_b32_e32 v119, v0
	v_mov_b32_e32 v120, v0
	v_mov_b32_e32 v121, v0
	v_mov_b32_e32 v122, v0
	v_mov_b32_e32 v123, v0
	v_mov_b32_e32 v124, v0
	v_mov_b32_e32 v125, v0
	v_mov_b32_e32 v126, v0
	v_mov_b32_e32 v127, v0
	v_mov_b32_e32 v128, v0
	v_mov_b32_e32 v129, v0
	v_readfirstlane_b32 s99, v164
	s_lshl_b32 s99, s99, 1
	.p2align 6

; DI int otid() { int t = threadIdx.x; asm volatile("" : "+v"(t)); return t; }
;   const int tid = otid();
;   const int lane = tid & 63, wid = tid >> 6, r = lane & 31, h = lane >> 5, wm = wid >> 1, wn = wid & 1;
;   bf16_t* sA = (bf16_t*)smem;
;   bf16_t* sB = sA;
;   float* sR = (float*)(smem + 73728);
;   const int m0 = tm << 8, n0 = tn << 7;
;   const bf16_t* Ag = A + (size_t)m0 * lda;
;   const bf16_t* Bg = Bt + (size_t)n0 * ldb;
;   if (ssq) {
;     const f32x4* sp = (const f32x4*)(ssq + (size_t)(m0 + tid) * 16);
;     const f32x4 a = sp[0], b = sp[1], c = sp[2], d = sp[3];
;     const float tot = ((a.x + a.y) + (a.z + a.w)) + ((b.x + b.y) + (b.z + b.w)) + ((c.x + c.y) + (c.z + c.w)) + ((d.x + d.y) + (d.z + d.w));
;     sR[tid] = rsqrtf(tot * (1.f / DM) + 1e-6f);
;   }
;   __syncthreads();
;     ...
;   for (int t = blockIdx.x; t < ntiles; t += gridDim.x) {
;     const int xcd = t & 7, j = t >> 3;
;     const int grp = j / (8 * nN), jj = j % (8 * nN);
;     const int tm = xcd * band + grp * 8 + (jj & 7), tn = jj >> 3;
.LBB0_512:
	s_ashr_i32 s9, s18, 31
	s_ashr_i32 s8, s18, 3
	s_lshr_b32 s9, s9, 26
	s_add_i32 s9, s8, s9
	s_ashr_i32 s27, s9, 6
	s_andn2_b32 s9, s9, 63
	s_sub_i32 s8, s8, s9
	s_and_b32 s9, s18, 7
	s_add_i32 s9, s27, s9
	v_mov_b32_e32 v143, v242
	s_lshl_b32 s20, s8, 8
	s_lshl_b32 s8, s8, 4
	s_lshl_b32 s9, s9, 11
	v_ashrrev_i32_e32 v145, 6, v143
	s_and_b32 s28, s20, 0x700
	s_and_b32 s21, s8, 0xffffff80
	v_bfe_u32 v144, v143, 5, 1
	s_or_b32 s20, s9, s28
	s_mul_i32 s8, s21, 0x440
	s_waitcnt vmcnt(0)
	v_and_b32_e32 v146, 31, v143
	v_and_b32_e32 v151, 1, v145
	v_lshrrev_b32_e32 v0, 2, v143
	s_and_b32 s26, s17, 7
	s_ashr_i32 s9, s8, 31
	s_mul_i32 s22, s20, 0x880
	v_lshlrev_b32_e32 v2, 6, v143
	v_lshlrev_b32_e32 v3, 6, v146
	v_lshlrev_b32_e32 v4, 12, v151
	v_bitop3_b32 v0, v0, v144, 3 bitop3:0x6c
	s_mul_hi_i32 s23, s20, 0x880
	s_add_u32 s22, s10, s22
	v_bfe_u32 v1, v143, 2, 2
	v_and_or_b32 v2, v2, s93, v3
	v_or3_b32 v3, v3, v4, s94
	v_lshlrev_b32_e32 v0, 4, v0
	v_bfe_u32 v142, v143, 4, 2
	s_addc_u32 s23, s11, s23
	s_lshl_b64 s[8:9], s[8:9], 1
	v_or_b32_e32 v147, v0, v2
	v_bitop3_b32 v1, v144, v1, 2 bitop3:0x36
	v_or_b32_e32 v149, v3, v0
	v_bitop3_b32 v0, v142, v143, 3 bitop3:0x78
	s_add_u32 s24, s12, s8
	v_lshlrev_b32_e32 v1, 4, v1
	s_mul_i32 s29, s19, 0x3000
	v_bfe_u32 v8, v143, 2, 4
	v_lshlrev_b32_e32 v32, 4, v0
	s_addc_u32 s25, s13, s9
	v_or_b32_e32 v148, v1, v2
	v_or_b32_e32 v150, v1, v3
	s_lshl_b32 s33, s29, 1
	v_lshl_add_u64 v[0:1], s[22:23], 0, v[32:33]
	v_lshl_or_b32 v12, v145, 4, v8
	v_lshlrev_b32_e32 v13, 10, v145
	v_mad_i64_i32 v[2:3], s[22:23], v12, s74, v[0:1]
	v_add_u32_e32 v14, s33, v13
	v_add_u32_e32 v6, 4, v145
	v_readfirstlane_b32 s22, v14
	v_lshl_or_b32 v15, v6, 4, v8
	v_lshlrev_b32_e32 v16, 10, v6
	s_mov_b32 m0, s22
	v_mad_i64_i32 v[4:5], s[22:23], v15, s74, v[0:1]
	v_add_u32_e32 v17, s33, v16
	v_add_u32_e32 v9, 8, v145
	v_lshlrev_b32_e32 v153, 9, v6
	v_readfirstlane_b32 s22, v17
	v_lshl_or_b32 v6, v9, 4, v8
	v_lshlrev_b32_e32 v154, 10, v9
	s_waitcnt lgkmcnt(0)
	s_barrier
; DI void dma_issue(const bf16_t* Ag, size_t lda, const bf16_t* Bg, size_t ldb, int kt, bf16_t* stage, int wid, int lane) {
;   const int rl = lane >> 2, c = (lane & 3) ^ ((lane >> 4) & 3);
; #pragma unroll
;   for (int i = 0; i < 4; ++i) {
;     const int j = wid + 4 * i;
;     __builtin_amdgcn_global_load_lds((const unsigned*)(Ag + (size_t)(16 * j + rl) * lda + kt * 32 + c * 8), (unsigned*)(stage + j * 512), 16, 0, 0);
;   }
; #pragma unroll
;   for (int i = 0; i < 2; ++i) {
;     const int j = wid + 4 * i;
;     __builtin_amdgcn_global_load_lds((const unsigned*)(Bg + (size_t)(16 * j + rl) * ldb + kt * 32 + c * 8), (unsigned*)(stage + STG_A + j * 512), 16, 0, 0);
;   }
; }
;     ...
;   f32x16 acc[4][2];
; #pragma unroll
;   for (int a = 0; a < 4; ++a)
; #pragma unroll
;     for (int b = 0; b < 2; ++b)
; #pragma unroll
;       for (int i = 0; i < 16; ++i) acc[a][b][i] = 0.f;
	global_load_lds_dwordx4 v[2:3], off
	s_mov_b32 m0, s22
	v_mad_i64_i32 v[6:7], s[22:23], v6, s74, v[0:1]
	v_add_u32_e32 v9, s33, v154
	global_load_lds_dwordx4 v[4:5], off
	v_readfirstlane_b32 s22, v9
	v_add_u32_e32 v9, 12, v145
	v_lshl_or_b32 v8, v9, 4, v8
	v_lshlrev_b32_e32 v155, 10, v9
	s_mov_b32 m0, s22
	v_mad_i64_i32 v[0:1], s[22:23], v8, s74, v[0:1]
	v_add_u32_e32 v8, s33, v155
	global_load_lds_dwordx4 v[6:7], off
	v_readfirstlane_b32 s22, v8
	v_lshl_add_u64 v[8:9], s[24:25], 0, v[32:33]
	s_mov_b32 m0, s22
	v_mad_i64_i32 v[10:11], s[22:23], v12, s74, v[8:9]
	v_add_u32_e32 v14, 0x4000, v14
	global_load_lds_dwordx4 v[0:1], off
	v_readfirstlane_b32 s22, v14
	s_mov_b32 m0, s22
	v_mad_i64_i32 v[8:9], s[22:23], v15, s74, v[8:9]
	v_add_u32_e32 v14, 0x4000, v17
	s_addk_i32 s29, 0x3000
	v_readfirstlane_b32 s22, v14
	s_cmp_lg_u32 s19, 2
	global_load_lds_dwordx4 v[10:11], off
	s_mov_b32 m0, s22
	s_cselect_b32 s22, s29, 0
	s_lshl_b32 s22, s22, 1
	v_add_u32_e32 v13, s22, v13
	global_load_lds_dwordx4 v[8:9], off
	v_readfirstlane_b32 s23, v13
	v_lshl_add_u64 v[2:3], v[2:3], 0, 64
	s_mov_b32 m0, s23
	v_lshl_add_u64 v[0:1], v[0:1], 0, 64
	global_load_lds_dwordx4 v[2:3], off
	v_lshl_add_u64 v[2:3], v[4:5], 0, 64
	v_add_u32_e32 v4, s22, v16
	v_add_u32_e32 v5, s22, v154
	v_readfirstlane_b32 s23, v4
	s_mov_b32 m0, s23
	v_readfirstlane_b32 s23, v5
	global_load_lds_dwordx4 v[2:3], off
	v_lshl_add_u64 v[2:3], v[6:7], 0, 64
	s_mov_b32 m0, s23
	s_add_u32 s8, s15, s8
	global_load_lds_dwordx4 v[2:3], off
	v_add_u32_e32 v2, s22, v155
	s_addc_u32 s9, s16, s9
	v_readfirstlane_b32 s22, v2
	v_add_u32_e32 v2, 0x4000, v13
	s_mov_b32 m0, s22
	v_readfirstlane_b32 s22, v2
	v_add_u32_e32 v2, 0x4000, v4
	global_load_lds_dwordx4 v[0:1], off
	v_lshl_add_u64 v[0:1], v[10:11], 0, 64
	s_mov_b32 m0, s22
	v_readfirstlane_b32 s22, v2
	global_load_lds_dwordx4 v[0:1], off
	v_lshl_add_u64 v[0:1], v[8:9], 0, 64
	s_mov_b32 m0, s22
	v_mad_i64_i32 v[2:3], s[22:23], v12, s74, 0
	global_load_lds_dwordx4 v[0:1], off
	v_add_u32_e32 v0, 64, v12
	v_mad_i64_i32 v[0:1], s[22:23], v0, s74, 0
	v_or_b32_e32 v0, v0, v32
	v_or_b32_e32 v2, v2, v32
	s_add_i32 s27, s27, s26
	v_lshl_add_u64 v[130:131], s[8:9], 0, v[0:1]
	v_lshl_add_u64 v[132:133], s[8:9], 0, v[2:3]
	s_lshl_b32 s8, s27, 11
	s_or_b32 s22, s8, s28
	s_mul_hi_i32 s9, s22, 0x880
	s_mul_i32 s8, s22, 0x880
	v_add_u32_e32 v6, 0xc0, v12
	v_mov_b64_e32 v[4:5], s[8:9]
	v_mad_i64_i32 v[6:7], s[8:9], v6, s74, v[4:5]
	v_or_b32_e32 v6, v6, v32
	v_lshl_add_u64 v[134:135], s[6:7], 0, v[6:7]
	v_add_u32_e32 v6, 0x80, v12
	v_mad_i64_i32 v[0:1], s[8:9], s22, v211, v[0:1]
	v_mad_i64_i32 v[4:5], s[8:9], v6, s74, v[4:5]
	v_lshl_add_u64 v[138:139], s[6:7], 0, v[0:1]
	v_mad_i64_i32 v[0:1], s[8:9], s22, v211, v[2:3]
	v_or_b32_e32 v4, v4, v32
	v_lshl_add_u64 v[140:141], s[6:7], 0, v[0:1]
	v_mov_b32_e32 v0, 0
	v_lshlrev_b32_e32 v152, 9, v145
	v_lshl_add_u64 v[136:137], s[6:7], 0, v[4:5]
	s_mov_b64 s[8:9], 0
	v_mov_b32_e32 v1, v0
	v_mov_b32_e32 v2, v0
	v_mov_b32_e32 v3, v0
	v_mov_b32_e32 v4, v0
	v_mov_b32_e32 v5, v0
	v_mov_b32_e32 v6, v0
	v_mov_b32_e32 v7, v0
	v_mov_b32_e32 v8, v0
	v_mov_b32_e32 v9, v0
	v_mov_b32_e32 v10, v0
	v_mov_b32_e32 v11, v0
	v_mov_b32_e32 v12, v0
	v_mov_b32_e32 v13, v0
	v_mov_b32_e32 v14, v0
	v_mov_b32_e32 v15, v0
	v_mov_b32_e32 v16, v0
	v_mov_b32_e32 v17, v0
	v_mov_b32_e32 v18, v0
	v_mov_b32_e32 v19, v0
	v_mov_b32_e32 v20, v0
	v_mov_b32_e32 v21, v0
	v_mov_b32_e32 v22, v0
	v_mov_b32_e32 v23, v0
	v_mov_b32_e32 v24, v0
	v_mov_b32_e32 v25, v0
	v_mov_b32_e32 v26, v0
	v_mov_b32_e32 v27, v0
	v_mov_b32_e32 v28, v0
	v_mov_b32_e32 v29, v0
	v_mov_b32_e32 v30, v0
	v_mov_b32_e32 v31, v0
	v_mov_b32_e32 v34, v0
	v_mov_b32_e32 v35, v0
	v_mov_b32_e32 v36, v0
	v_mov_b32_e32 v37, v0
	v_mov_b32_e32 v38, v0
	v_mov_b32_e32 v39, v0
	v_mov_b32_e32 v40, v0
	v_mov_b32_e32 v41, v0
	v_mov_b32_e32 v42, v0
	v_mov_b32_e32 v43, v0
	v_mov_b32_e32 v44, v0
	v_mov_b32_e32 v45, v0
	v_mov_b32_e32 v46, v0
	v_mov_b32_e32 v47, v0
	v_mov_b32_e32 v48, v0
	v_mov_b32_e32 v49, v0
	v_mov_b32_e32 v50, v0
	v_mov_b32_e32 v51, v0
	v_mov_b32_e32 v52, v0
	v_mov_b32_e32 v53, v0
	v_mov_b32_e32 v54, v0
	v_mov_b32_e32 v55, v0
	v_mov_b32_e32 v56, v0
	v_mov_b32_e32 v57, v0
	v_mov_b32_e32 v58, v0
	v_mov_b32_e32 v59, v0
	v_mov_b32_e32 v60, v0
	v_mov_b32_e32 v61, v0
	v_mov_b32_e32 v62, v0
	v_mov_b32_e32 v63, v0
	v_mov_b32_e32 v64, v0
	v_mov_b32_e32 v65, v0
	v_mov_b32_e32 v66, v0
	v_mov_b32_e32 v67, v0
	v_mov_b32_e32 v68, v0
	v_mov_b32_e32 v69, v0
	v_mov_b32_e32 v70, v0
	v_mov_b32_e32 v71, v0
	v_mov_b32_e32 v72, v0
	v_mov_b32_e32 v73, v0
	v_mov_b32_e32 v74, v0
	v_mov_b32_e32 v75, v0
	v_mov_b32_e32 v76, v0
	v_mov_b32_e32 v77, v0
	v_mov_b32_e32 v78, v0
	v_mov_b32_e32 v79, v0
	v_mov_b32_e32 v80, v0
	v_mov_b32_e32 v81, v0
	v_mov_b32_e32 v82, v0
	v_mov_b32_e32 v83, v0
	v_mov_b32_e32 v84, v0
	v_mov_b32_e32 v85, v0
	v_mov_b32_e32 v86, v0
	v_mov_b32_e32 v87, v0
	v_mov_b32_e32 v88, v0
	v_mov_b32_e32 v89, v0
	v_mov_b32_e32 v90, v0
	v_mov_b32_e32 v91, v0
	v_mov_b32_e32 v92, v0
	v_mov_b32_e32 v93, v0
	v_mov_b32_e32 v94, v0
	v_mov_b32_e32 v95, v0
	v_mov_b32_e32 v96, v0
	v_mov_b32_e32 v97, v0
	s_waitcnt vmcnt(0)
	v_mov_b32_e32 v98, v0
	v_mov_b32_e32 v99, v0
	v_mov_b32_e32 v100, v0
	v_mov_b32_e32 v101, v0
	v_mov_b32_e32 v102, v0
	v_mov_b32_e32 v103, v0
	v_mov_b32_e32 v104, v0
	v_mov_b32_e32 v105, v0
	v_mov_b32_e32 v106, v0
	v_mov_b32_e32 v107, v0
	v_mov_b32_e32 v108, v0
	v_mov_b32_e32 v109, v0
	v_mov_b32_e32 v110, v0
	v_mov_b32_e32 v111, v0
	v_mov_b32_e32 v112, v0
	v_mov_b32_e32 v113, v0
	v_mov_b32_e32 v114, v0
	v_mov_b32_e32 v115, v0
	v_mov_b32_e32 v116, v0
	v_mov_b32_e32 v117, v0
	v_mov_b32_e32 v118, v0
	v_mov_b32_e32 v119, v0
	v_mov_b32_e32 v120, v0
	v_mov_b32_e32 v121, v0
	v_mov_b32_e32 v122, v0
	v_mov_b32_e32 v123, v0
	v_mov_b32_e32 v124, v0
	v_mov_b32_e32 v125, v0
	v_mov_b32_e32 v126, v0
	v_mov_b32_e32 v127, v0
	v_mov_b32_e32 v128, v0
	v_mov_b32_e32 v129, v0
	v_readfirstlane_b32 s99, v152
	s_lshl_b32 s99, s99, 1
	.p2align 6

;     ...
;   f32x16 acc[4][2];
; #pragma unroll
;   for (int a = 0; a < 4; ++a)
; #pragma unroll
;     for (int b = 0; b < 2; ++b)
; #pragma unroll
;       for (int i = 0; i < 16; ++i) acc[a][b][i] = 0.f;
;   const bool vt = epi.vtype(n0 + wn * 64);
;   int st_last = 0;
;   if (pm == 2) K >>= 1;
;   if (DEEP) {
;     const bf16_t* AgN = tmN >= 0 ? A + (size_t)(tmN << 8) * lda : nullptr;
;     const bf16_t* BgN = Bt + (size_t)(tnN << 7) * ldb;
;     if (vt) st_last = gemm_kloop<true>(Ag, lda, Bg, ldb, K >> 5, sA, acc, tid, wm, wn, r, h, st0, pre, AgN, BgN);
;     else st_last = gemm_kloop<false>(Ag, lda, Bg, ldb, K >> 5, sA, acc, tid, wm, wn, r, h, st0, pre, AgN, BgN);
.LBB0_644:
	v_lshlrev_b64 v[138:139], 1, v[32:33]
	s_add_u32 s46, s63, s52
	v_lshlrev_b32_e32 v165, 10, v0
	v_lshlrev_b32_e32 v164, 10, v1
	v_lshl_add_u64 v[0:1], v[132:133], 1, v[138:139]
	s_addc_u32 s47, s64, s53
	v_lshl_add_u64 v[2:3], v[130:131], 1, v[138:139]
	v_lshl_add_u64 v[140:141], s[46:47], 0, v[0:1]
	v_lshl_add_u64 v[142:143], s[46:47], 0, v[2:3]
	s_add_i32 s46, s50, s54
	s_lshl_b32 s46, s46, 11
	s_or_b32 s55, s46, s51
	v_lshlrev_b64 v[4:5], 1, v[136:137]
	v_mad_i64_i32 v[4:5], s[46:47], s55, v211, v[4:5]
	v_lshl_add_u64 v[4:5], v[4:5], 0, v[138:139]
	v_lshl_add_u64 v[144:145], s[28:29], 0, v[4:5]
	v_lshlrev_b64 v[4:5], 1, v[134:135]
	v_mad_i64_i32 v[4:5], s[46:47], s55, v211, v[4:5]
	v_mad_i64_i32 v[0:1], s[46:47], s55, v211, v[0:1]
	v_lshl_add_u64 v[4:5], v[4:5], 0, v[138:139]
	v_lshl_add_u64 v[148:149], s[28:29], 0, v[0:1]
	v_mad_i64_i32 v[0:1], s[46:47], s55, v211, v[2:3]
	v_mov_b32_e32 v16, 0
	v_lshl_add_u64 v[146:147], s[28:29], 0, v[4:5]
	v_lshl_add_u64 v[150:151], s[28:29], 0, v[0:1]
	s_mov_b64 s[46:47], 0
	s_mov_b32 s55, s48
	v_mov_b32_e32 v17, v16
	v_mov_b32_e32 v18, v16
	v_mov_b32_e32 v19, v16
	v_mov_b32_e32 v20, v16
	v_mov_b32_e32 v21, v16
	v_mov_b32_e32 v22, v16
	v_mov_b32_e32 v23, v16
	v_mov_b32_e32 v24, v16
	v_mov_b32_e32 v25, v16
	v_mov_b32_e32 v26, v16
	v_mov_b32_e32 v27, v16
	v_mov_b32_e32 v28, v16
	v_mov_b32_e32 v29, v16
	v_mov_b32_e32 v30, v16
	v_mov_b32_e32 v31, v16
	v_mov_b32_e32 v0, v16
	v_mov_b32_e32 v1, v16
	v_mov_b32_e32 v2, v16
	v_mov_b32_e32 v3, v16
	v_mov_b32_e32 v4, v16
	v_mov_b32_e32 v5, v16
	v_mov_b32_e32 v6, v16
	v_mov_b32_e32 v7, v16
	v_mov_b32_e32 v8, v16
	v_mov_b32_e32 v9, v16
	v_mov_b32_e32 v10, v16
	v_mov_b32_e32 v11, v16
	v_mov_b32_e32 v12, v16
	v_mov_b32_e32 v13, v16
	v_mov_b32_e32 v14, v16
	v_mov_b32_e32 v15, v16
	v_mov_b32_e32 v50, v16
	v_mov_b32_e32 v51, v16
	v_mov_b32_e32 v52, v16
	v_mov_b32_e32 v53, v16
	v_mov_b32_e32 v54, v16
	v_mov_b32_e32 v55, v16
	v_mov_b32_e32 v56, v16
	v_mov_b32_e32 v57, v16
	v_mov_b32_e32 v58, v16
	v_mov_b32_e32 v59, v16
	v_mov_b32_e32 v60, v16
	v_mov_b32_e32 v61, v16
	v_mov_b32_e32 v62, v16
	v_mov_b32_e32 v63, v16
	v_mov_b32_e32 v64, v16
	v_mov_b32_e32 v65, v16
	v_mov_b32_e32 v34, v16
	v_mov_b32_e32 v35, v16
	v_mov_b32_e32 v36, v16
	v_mov_b32_e32 v37, v16
	v_mov_b32_e32 v38, v16
	v_mov_b32_e32 v39, v16
	v_mov_b32_e32 v40, v16
	v_mov_b32_e32 v41, v16
	v_mov_b32_e32 v42, v16
	v_mov_b32_e32 v43, v16
	v_mov_b32_e32 v44, v16
	v_mov_b32_e32 v45, v16
	v_mov_b32_e32 v46, v16
	v_mov_b32_e32 v47, v16
	v_mov_b32_e32 v48, v16
	v_mov_b32_e32 v49, v16
	v_mov_b32_e32 v82, v16
	v_mov_b32_e32 v83, v16
	v_mov_b32_e32 v84, v16
	v_mov_b32_e32 v85, v16
	v_mov_b32_e32 v86, v16
	v_mov_b32_e32 v87, v16
	v_mov_b32_e32 v88, v16
	v_mov_b32_e32 v89, v16
	v_mov_b32_e32 v90, v16
	v_mov_b32_e32 v91, v16
	v_mov_b32_e32 v92, v16
	v_mov_b32_e32 v93, v16
	v_mov_b32_e32 v94, v16
	v_mov_b32_e32 v95, v16
	v_mov_b32_e32 v96, v16
	v_mov_b32_e32 v97, v16
	v_mov_b32_e32 v66, v16
	v_mov_b32_e32 v67, v16
	v_mov_b32_e32 v68, v16
	v_mov_b32_e32 v69, v16
	v_mov_b32_e32 v70, v16
	v_mov_b32_e32 v71, v16
	v_mov_b32_e32 v72, v16
	v_mov_b32_e32 v73, v16
	v_mov_b32_e32 v74, v16
	v_mov_b32_e32 v75, v16
	v_mov_b32_e32 v76, v16
	v_mov_b32_e32 v77, v16
	v_mov_b32_e32 v78, v16
	v_mov_b32_e32 v79, v16
	v_mov_b32_e32 v80, v16
	v_mov_b32_e32 v81, v16
	v_mov_b32_e32 v114, v16
	v_mov_b32_e32 v115, v16
	v_mov_b32_e32 v116, v16
	v_mov_b32_e32 v117, v16
	v_mov_b32_e32 v118, v16
	v_mov_b32_e32 v119, v16
	v_mov_b32_e32 v120, v16
	v_mov_b32_e32 v121, v16
	v_mov_b32_e32 v122, v16
	v_mov_b32_e32 v123, v16
	v_mov_b32_e32 v124, v16
	v_mov_b32_e32 v125, v16
	v_mov_b32_e32 v126, v16
	v_mov_b32_e32 v127, v16
	v_mov_b32_e32 v128, v16
	v_mov_b32_e32 v129, v16
	v_mov_b32_e32 v98, v16
	v_mov_b32_e32 v99, v16
	v_mov_b32_e32 v100, v16
	v_mov_b32_e32 v101, v16
	v_mov_b32_e32 v102, v16
	v_mov_b32_e32 v103, v16
	v_mov_b32_e32 v104, v16
	v_mov_b32_e32 v105, v16
	v_mov_b32_e32 v106, v16
	v_mov_b32_e32 v107, v16
	v_mov_b32_e32 v108, v16
	v_mov_b32_e32 v109, v16
	v_mov_b32_e32 v110, v16
	v_mov_b32_e32 v111, v16
	v_mov_b32_e32 v112, v16
	v_mov_b32_e32 v113, v16
	v_readfirstlane_b32 s99, v162
	s_lshl_b32 s99, s99, 1
	.p2align 6

;     ...
;   f32x16 acc[4][2];
; #pragma unroll
;   for (int a = 0; a < 4; ++a)
; #pragma unroll
;     for (int b = 0; b < 2; ++b)
; #pragma unroll
;       for (int i = 0; i < 16; ++i) acc[a][b][i] = 0.f;
;   const bool vt = epi.vtype(n0 + wn * 64);
;   int st_last = 0;
;   if (pm == 2) K >>= 1;
;   if (DEEP) {
;     const bf16_t* AgN = tmN >= 0 ? A + (size_t)(tmN << 8) * lda : nullptr;
;     const bf16_t* BgN = Bt + (size_t)(tnN << 7) * ldb;
;     if (vt) st_last = gemm_kloop<true>(Ag, lda, Bg, ldb, K >> 5, sA, acc, tid, wm, wn, r, h, st0, pre, AgN, BgN);
;     else st_last = gemm_kloop<false>(Ag, lda, Bg, ldb, K >> 5, sA, acc, tid, wm, wn, r, h, st0, pre, AgN, BgN);
.LBB0_654:
	v_lshlrev_b64 v[138:139], 1, v[32:33]
	s_add_u32 s40, s63, s52
	v_lshl_add_u64 v[0:1], v[132:133], 1, v[138:139]
	s_addc_u32 s41, s64, s53
	v_lshl_add_u64 v[2:3], v[130:131], 1, v[138:139]
	s_add_i32 s50, s50, s54
	v_lshl_add_u64 v[140:141], s[40:41], 0, v[0:1]
	v_lshl_add_u64 v[142:143], s[40:41], 0, v[2:3]
	s_lshl_b32 s40, s50, 11
	s_or_b32 s42, s40, s51
	v_lshlrev_b64 v[4:5], 1, v[136:137]
	v_mad_i64_i32 v[4:5], s[40:41], s42, v211, v[4:5]
	v_lshl_add_u64 v[4:5], v[4:5], 0, v[138:139]
	v_lshl_add_u64 v[144:145], s[28:29], 0, v[4:5]
	v_lshlrev_b64 v[4:5], 1, v[134:135]
	v_mad_i64_i32 v[4:5], s[40:41], s42, v211, v[4:5]
	v_mad_i64_i32 v[0:1], s[40:41], s42, v211, v[0:1]
	v_lshl_add_u64 v[4:5], v[4:5], 0, v[138:139]
	v_lshl_add_u64 v[148:149], s[28:29], 0, v[0:1]
	v_mad_i64_i32 v[0:1], s[40:41], s42, v211, v[2:3]
	v_mov_b32_e32 v16, 0
	v_lshlrev_b32_e32 v164, 10, v8
	v_lshlrev_b32_e32 v163, 10, v10
	v_lshl_add_u64 v[146:147], s[28:29], 0, v[4:5]
	v_lshl_add_u64 v[150:151], s[28:29], 0, v[0:1]
	s_mov_b64 s[40:41], 0
	v_mov_b32_e32 v17, v16
	v_mov_b32_e32 v18, v16
	v_mov_b32_e32 v19, v16
	v_mov_b32_e32 v20, v16
	v_mov_b32_e32 v21, v16
	v_mov_b32_e32 v22, v16
	v_mov_b32_e32 v23, v16
	v_mov_b32_e32 v24, v16
	v_mov_b32_e32 v25, v16
	v_mov_b32_e32 v26, v16
	v_mov_b32_e32 v27, v16
	v_mov_b32_e32 v28, v16
	v_mov_b32_e32 v29, v16
	v_mov_b32_e32 v30, v16
	v_mov_b32_e32 v31, v16
	v_mov_b32_e32 v0, v16
	v_mov_b32_e32 v1, v16
	v_mov_b32_e32 v2, v16
	v_mov_b32_e32 v3, v16
	v_mov_b32_e32 v4, v16
	v_mov_b32_e32 v5, v16
	v_mov_b32_e32 v6, v16
	v_mov_b32_e32 v7, v16
	v_mov_b32_e32 v8, v16
	v_mov_b32_e32 v9, v16
	v_mov_b32_e32 v10, v16
	v_mov_b32_e32 v11, v16
	v_mov_b32_e32 v12, v16
	v_mov_b32_e32 v13, v16
	v_mov_b32_e32 v14, v16
	v_mov_b32_e32 v15, v16
	v_mov_b32_e32 v50, v16
	v_mov_b32_e32 v51, v16
	v_mov_b32_e32 v52, v16
	v_mov_b32_e32 v53, v16
	v_mov_b32_e32 v54, v16
	v_mov_b32_e32 v55, v16
	v_mov_b32_e32 v56, v16
	v_mov_b32_e32 v57, v16
	v_mov_b32_e32 v58, v16
	v_mov_b32_e32 v59, v16
	v_mov_b32_e32 v60, v16
	v_mov_b32_e32 v61, v16
	v_mov_b32_e32 v62, v16
	v_mov_b32_e32 v63, v16
	v_mov_b32_e32 v64, v16
	v_mov_b32_e32 v65, v16
	v_mov_b32_e32 v34, v16
	v_mov_b32_e32 v35, v16
	v_mov_b32_e32 v36, v16
	v_mov_b32_e32 v37, v16
	v_mov_b32_e32 v38, v16
	v_mov_b32_e32 v39, v16
	v_mov_b32_e32 v40, v16
	v_mov_b32_e32 v41, v16
	v_mov_b32_e32 v42, v16
	v_mov_b32_e32 v43, v16
	v_mov_b32_e32 v44, v16
	v_mov_b32_e32 v45, v16
	v_mov_b32_e32 v46, v16
	v_mov_b32_e32 v47, v16
	v_mov_b32_e32 v48, v16
	v_mov_b32_e32 v49, v16
	v_mov_b32_e32 v82, v16
	v_mov_b32_e32 v83, v16
	v_mov_b32_e32 v84, v16
	v_mov_b32_e32 v85, v16
	v_mov_b32_e32 v86, v16
	v_mov_b32_e32 v87, v16
	v_mov_b32_e32 v88, v16
	v_mov_b32_e32 v89, v16
	v_mov_b32_e32 v90, v16
	v_mov_b32_e32 v91, v16
	v_mov_b32_e32 v92, v16
	v_mov_b32_e32 v93, v16
	v_mov_b32_e32 v94, v16
	v_mov_b32_e32 v95, v16
	v_mov_b32_e32 v96, v16
	v_mov_b32_e32 v97, v16
	v_mov_b32_e32 v66, v16
	v_mov_b32_e32 v67, v16
	v_mov_b32_e32 v68, v16
	v_mov_b32_e32 v69, v16
	v_mov_b32_e32 v70, v16
	v_mov_b32_e32 v71, v16
	v_mov_b32_e32 v72, v16
	v_mov_b32_e32 v73, v16
	v_mov_b32_e32 v74, v16
	v_mov_b32_e32 v75, v16
	v_mov_b32_e32 v76, v16
	v_mov_b32_e32 v77, v16
	v_mov_b32_e32 v78, v16
	v_mov_b32_e32 v79, v16
	v_mov_b32_e32 v80, v16
	v_mov_b32_e32 v81, v16
	v_mov_b32_e32 v114, v16
	v_mov_b32_e32 v115, v16
	v_mov_b32_e32 v116, v16
	v_mov_b32_e32 v117, v16
	v_mov_b32_e32 v118, v16
	v_mov_b32_e32 v119, v16
	v_mov_b32_e32 v120, v16
	v_mov_b32_e32 v121, v16
	v_mov_b32_e32 v122, v16
	v_mov_b32_e32 v123, v16
	v_mov_b32_e32 v124, v16
	v_mov_b32_e32 v125, v16
	v_mov_b32_e32 v126, v16
	v_mov_b32_e32 v127, v16
	v_mov_b32_e32 v128, v16
	v_mov_b32_e32 v129, v16
	v_mov_b32_e32 v98, v16
	v_mov_b32_e32 v99, v16
	v_mov_b32_e32 v100, v16
	v_mov_b32_e32 v101, v16
	v_mov_b32_e32 v102, v16
	v_mov_b32_e32 v103, v16
	v_mov_b32_e32 v104, v16
	v_mov_b32_e32 v105, v16
	v_mov_b32_e32 v106, v16
	v_mov_b32_e32 v107, v16
	v_mov_b32_e32 v108, v16
	v_mov_b32_e32 v109, v16
	v_mov_b32_e32 v110, v16
	v_mov_b32_e32 v111, v16
	v_mov_b32_e32 v112, v16
	v_mov_b32_e32 v113, v16
	v_readfirstlane_b32 s99, v162
	s_lshl_b32 s99, s99, 1
	.p2align 6

; DI int otid() { int t = threadIdx.x; asm volatile("" : "+v"(t)); return t; }
;   const int tid = otid();
;   const int lane = tid & 63, wid = tid >> 6, r = lane & 31, h = lane >> 5, wm = wid >> 1, wn = wid & 1;
;   bf16_t* sA = (bf16_t*)smem;
;   bf16_t* sB = sA;
;   float* sR = (float*)(smem + 73728);
;   const int m0 = tm << 8, n0 = tn << 7;
;   const bf16_t* Ag = A + (size_t)m0 * lda;
;   const bf16_t* Bg = Bt + (size_t)n0 * ldb;
;   if (ssq) {
;     const f32x4* sp = (const f32x4*)(ssq + (size_t)(m0 + tid) * 16);
;     const f32x4 a = sp[0], b = sp[1], c = sp[2], d = sp[3];
;     const float tot = ((a.x + a.y) + (a.z + a.w)) + ((b.x + b.y) + (b.z + b.w)) + ((c.x + c.y) + (c.z + c.w)) + ((d.x + d.y) + (d.z + d.w));
;     sR[tid] = rsqrtf(tot * (1.f / DM) + 1e-6f);
;   }
;   __syncthreads();
;     ...
;   for (int t = blockIdx.x; t < ntiles; t += gridDim.x) {
;     const int xcd = t & 7, j = t >> 3;
;     const int grp = j / (8 * nN), jj = j % (8 * nN);
;     const int tm = xcd * band + grp * 8 + (jj & 7), tn = jj >> 3;
.LBB0_1136:
	s_ashr_i32 s11, s20, 31
	s_ashr_i32 s10, s20, 3
	s_lshr_b32 s11, s11, 26
	s_add_i32 s11, s10, s11
	s_ashr_i32 s29, s11, 6
	s_andn2_b32 s11, s11, 63
	s_sub_i32 s10, s10, s11
	s_and_b32 s11, s20, 7
	s_add_i32 s11, s29, s11
	v_mov_b32_e32 v144, v242
	s_lshl_b32 s22, s10, 8
	s_lshl_b32 s10, s10, 4
	s_lshl_b32 s11, s11, 11
	v_ashrrev_i32_e32 v145, 6, v144
	s_and_b32 s30, s22, 0x700
	s_and_b32 s23, s10, 0xffffff80
	v_bfe_u32 v143, v144, 5, 1
	s_or_b32 s22, s11, s30
	s_mul_i32 s10, s23, 0x440
	s_waitcnt vmcnt(0)
	v_and_b32_e32 v146, 31, v144
	v_and_b32_e32 v151, 1, v145
	v_lshrrev_b32_e32 v0, 2, v144
	s_and_b32 s28, s19, 7
	s_ashr_i32 s11, s10, 31
	s_mul_i32 s24, s22, 0x880
	v_lshlrev_b32_e32 v2, 6, v144
	v_lshlrev_b32_e32 v3, 6, v146
	v_lshlrev_b32_e32 v4, 12, v151
	v_bitop3_b32 v0, v0, v143, 3 bitop3:0x6c
	s_mul_hi_i32 s25, s22, 0x880
	s_add_u32 s24, s12, s24
	v_bfe_u32 v1, v144, 2, 2
	v_and_or_b32 v2, v2, s93, v3
	v_or3_b32 v3, v3, v4, s94
	v_lshlrev_b32_e32 v0, 4, v0
	v_bfe_u32 v142, v144, 4, 2
	s_addc_u32 s25, s13, s25
	s_lshl_b64 s[10:11], s[10:11], 1
	v_or_b32_e32 v147, v0, v2
	v_bitop3_b32 v1, v143, v1, 2 bitop3:0x36
	v_or_b32_e32 v149, v3, v0
	v_bitop3_b32 v0, v142, v144, 3 bitop3:0x78
	s_add_u32 s26, s14, s10
	v_lshlrev_b32_e32 v1, 4, v1
	s_mul_i32 s31, s21, 0x3000
	v_bfe_u32 v8, v144, 2, 4
	v_lshlrev_b32_e32 v32, 4, v0
	s_addc_u32 s27, s15, s11
	v_or_b32_e32 v148, v1, v2
	v_or_b32_e32 v150, v1, v3
	s_lshl_b32 s33, s31, 1
	v_lshl_add_u64 v[0:1], s[24:25], 0, v[32:33]
	v_lshl_or_b32 v12, v145, 4, v8
	v_lshlrev_b32_e32 v13, 10, v145
	v_mad_i64_i32 v[2:3], s[24:25], v12, s74, v[0:1]
	v_add_u32_e32 v14, s33, v13
	v_add_u32_e32 v6, 4, v145
	v_readfirstlane_b32 s24, v14
	v_lshl_or_b32 v15, v6, 4, v8
	v_lshlrev_b32_e32 v16, 10, v6
	s_mov_b32 m0, s24
	v_mad_i64_i32 v[4:5], s[24:25], v15, s74, v[0:1]
	v_add_u32_e32 v17, s33, v16
	v_add_u32_e32 v9, 8, v145
	v_lshlrev_b32_e32 v153, 9, v6
	v_readfirstlane_b32 s24, v17
	v_lshl_or_b32 v6, v9, 4, v8
	v_lshlrev_b32_e32 v154, 10, v9
	s_waitcnt lgkmcnt(0)
	s_barrier
; DI void dma_issue(const bf16_t* Ag, size_t lda, const bf16_t* Bg, size_t ldb, int kt, bf16_t* stage, int wid, int lane) {
;   const int rl = lane >> 2, c = (lane & 3) ^ ((lane >> 4) & 3);
; #pragma unroll
;   for (int i = 0; i < 4; ++i) {
;     const int j = wid + 4 * i;
;     __builtin_amdgcn_global_load_lds((const unsigned*)(Ag + (size_t)(16 * j + rl) * lda + kt * 32 + c * 8), (unsigned*)(stage + j * 512), 16, 0, 0);
;   }
; #pragma unroll
;   for (int i = 0; i < 2; ++i) {
;     const int j = wid + 4 * i;
;     __builtin_amdgcn_global_load_lds((const unsigned*)(Bg + (size_t)(16 * j + rl) * ldb + kt * 32 + c * 8), (unsigned*)(stage + STG_A + j * 512), 16, 0, 0);
;   }
; }
;     ...
;   f32x16 acc[4][2];
; #pragma unroll
;   for (int a = 0; a < 4; ++a)
; #pragma unroll
;     for (int b = 0; b < 2; ++b)
; #pragma unroll
;       for (int i = 0; i < 16; ++i) acc[a][b][i] = 0.f;
	global_load_lds_dwordx4 v[2:3], off
	s_mov_b32 m0, s24
	v_mad_i64_i32 v[6:7], s[24:25], v6, s74, v[0:1]
	v_add_u32_e32 v9, s33, v154
	global_load_lds_dwordx4 v[4:5], off
	v_readfirstlane_b32 s24, v9
	v_add_u32_e32 v9, 12, v145
	v_lshl_or_b32 v8, v9, 4, v8
	v_lshlrev_b32_e32 v155, 10, v9
	s_mov_b32 m0, s24
	v_mad_i64_i32 v[0:1], s[24:25], v8, s74, v[0:1]
	v_add_u32_e32 v8, s33, v155
	global_load_lds_dwordx4 v[6:7], off
	v_readfirstlane_b32 s24, v8
	v_lshl_add_u64 v[8:9], s[26:27], 0, v[32:33]
	s_mov_b32 m0, s24
	v_mad_i64_i32 v[10:11], s[24:25], v12, s74, v[8:9]
	v_add_u32_e32 v14, 0x4000, v14
	global_load_lds_dwordx4 v[0:1], off
	v_readfirstlane_b32 s24, v14
	s_mov_b32 m0, s24
	v_mad_i64_i32 v[8:9], s[24:25], v15, s74, v[8:9]
	v_add_u32_e32 v14, 0x4000, v17
	s_addk_i32 s31, 0x3000
	v_readfirstlane_b32 s24, v14
	s_cmp_lg_u32 s21, 2
	global_load_lds_dwordx4 v[10:11], off
	s_mov_b32 m0, s24
	s_cselect_b32 s24, s31, 0
	s_lshl_b32 s24, s24, 1
	v_add_u32_e32 v13, s24, v13
	global_load_lds_dwordx4 v[8:9], off
	v_readfirstlane_b32 s25, v13
	v_lshl_add_u64 v[2:3], v[2:3], 0, 64
	s_mov_b32 m0, s25
	v_lshl_add_u64 v[0:1], v[0:1], 0, 64
	global_load_lds_dwordx4 v[2:3], off
	v_lshl_add_u64 v[2:3], v[4:5], 0, 64
	v_add_u32_e32 v4, s24, v16
	v_add_u32_e32 v5, s24, v154
	v_readfirstlane_b32 s25, v4
	s_mov_b32 m0, s25
	v_readfirstlane_b32 s25, v5
	global_load_lds_dwordx4 v[2:3], off
	v_lshl_add_u64 v[2:3], v[6:7], 0, 64
	s_mov_b32 m0, s25
	s_add_u32 s10, s17, s10
	global_load_lds_dwordx4 v[2:3], off
	v_add_u32_e32 v2, s24, v155
	s_addc_u32 s11, s18, s11
	v_readfirstlane_b32 s24, v2
	v_add_u32_e32 v2, 0x4000, v13
	s_mov_b32 m0, s24
	v_readfirstlane_b32 s24, v2
	v_add_u32_e32 v2, 0x4000, v4
	global_load_lds_dwordx4 v[0:1], off
	v_lshl_add_u64 v[0:1], v[10:11], 0, 64
	s_mov_b32 m0, s24
	v_readfirstlane_b32 s24, v2
	global_load_lds_dwordx4 v[0:1], off
	v_lshl_add_u64 v[0:1], v[8:9], 0, 64
	s_mov_b32 m0, s24
	v_mad_i64_i32 v[2:3], s[24:25], v12, s74, 0
	global_load_lds_dwordx4 v[0:1], off
	v_add_u32_e32 v0, 64, v12
	v_mad_i64_i32 v[0:1], s[24:25], v0, s74, 0
	v_or_b32_e32 v0, v0, v32
	v_or_b32_e32 v2, v2, v32
	s_add_i32 s29, s29, s28
	v_lshl_add_u64 v[130:131], s[10:11], 0, v[0:1]
	v_lshl_add_u64 v[132:133], s[10:11], 0, v[2:3]
	s_lshl_b32 s10, s29, 11
	s_or_b32 s24, s10, s30
	s_mul_hi_i32 s11, s24, 0x880
	s_mul_i32 s10, s24, 0x880
	v_add_u32_e32 v6, 0xc0, v12
	v_mov_b64_e32 v[4:5], s[10:11]
	v_mad_i64_i32 v[6:7], s[10:11], v6, s74, v[4:5]
	v_or_b32_e32 v6, v6, v32
	v_lshl_add_u64 v[134:135], s[8:9], 0, v[6:7]
	v_add_u32_e32 v6, 0x80, v12
	v_mad_i64_i32 v[0:1], s[10:11], s24, v211, v[0:1]
	v_mad_i64_i32 v[4:5], s[10:11], v6, s74, v[4:5]
	v_lshl_add_u64 v[138:139], s[8:9], 0, v[0:1]
	v_mad_i64_i32 v[0:1], s[10:11], s24, v211, v[2:3]
	v_or_b32_e32 v4, v4, v32
	v_lshl_add_u64 v[140:141], s[8:9], 0, v[0:1]
	v_mov_b32_e32 v0, 0
	v_lshlrev_b32_e32 v152, 9, v145
	v_lshl_add_u64 v[136:137], s[8:9], 0, v[4:5]
	s_mov_b64 s[10:11], 0
	v_mov_b32_e32 v1, v0
	v_mov_b32_e32 v2, v0
	v_mov_b32_e32 v3, v0
	v_mov_b32_e32 v4, v0
	v_mov_b32_e32 v5, v0
	v_mov_b32_e32 v6, v0
	v_mov_b32_e32 v7, v0
	v_mov_b32_e32 v8, v0
	v_mov_b32_e32 v9, v0
	v_mov_b32_e32 v10, v0
	v_mov_b32_e32 v11, v0
	v_mov_b32_e32 v12, v0
	v_mov_b32_e32 v13, v0
	v_mov_b32_e32 v14, v0
	v_mov_b32_e32 v15, v0
	v_mov_b32_e32 v16, v0
	v_mov_b32_e32 v17, v0
	v_mov_b32_e32 v18, v0
	v_mov_b32_e32 v19, v0
	v_mov_b32_e32 v20, v0
	v_mov_b32_e32 v21, v0
	v_mov_b32_e32 v22, v0
	v_mov_b32_e32 v23, v0
	v_mov_b32_e32 v24, v0
	v_mov_b32_e32 v25, v0
	v_mov_b32_e32 v26, v0
	v_mov_b32_e32 v27, v0
	v_mov_b32_e32 v28, v0
	v_mov_b32_e32 v29, v0
	v_mov_b32_e32 v30, v0
	v_mov_b32_e32 v31, v0
	v_mov_b32_e32 v34, v0
	v_mov_b32_e32 v35, v0
	v_mov_b32_e32 v36, v0
	v_mov_b32_e32 v37, v0
	v_mov_b32_e32 v38, v0
	v_mov_b32_e32 v39, v0
	v_mov_b32_e32 v40, v0
	v_mov_b32_e32 v41, v0
	v_mov_b32_e32 v42, v0
	v_mov_b32_e32 v43, v0
	v_mov_b32_e32 v44, v0
	v_mov_b32_e32 v45, v0
	v_mov_b32_e32 v46, v0
	v_mov_b32_e32 v47, v0
	v_mov_b32_e32 v48, v0
	v_mov_b32_e32 v49, v0
	v_mov_b32_e32 v50, v0
	v_mov_b32_e32 v51, v0
	v_mov_b32_e32 v52, v0
	v_mov_b32_e32 v53, v0
	v_mov_b32_e32 v54, v0
	v_mov_b32_e32 v55, v0
	v_mov_b32_e32 v56, v0
	v_mov_b32_e32 v57, v0
	v_mov_b32_e32 v58, v0
	v_mov_b32_e32 v59, v0
	v_mov_b32_e32 v60, v0
	v_mov_b32_e32 v61, v0
	v_mov_b32_e32 v62, v0
	v_mov_b32_e32 v63, v0
	v_mov_b32_e32 v64, v0
	v_mov_b32_e32 v65, v0
	v_mov_b32_e32 v66, v0
	v_mov_b32_e32 v67, v0
	v_mov_b32_e32 v68, v0
	v_mov_b32_e32 v69, v0
	v_mov_b32_e32 v70, v0
	v_mov_b32_e32 v71, v0
	v_mov_b32_e32 v72, v0
	v_mov_b32_e32 v73, v0
	v_mov_b32_e32 v74, v0
	v_mov_b32_e32 v75, v0
	v_mov_b32_e32 v76, v0
	v_mov_b32_e32 v77, v0
	v_mov_b32_e32 v78, v0
	v_mov_b32_e32 v79, v0
	v_mov_b32_e32 v80, v0
	v_mov_b32_e32 v81, v0
	v_mov_b32_e32 v82, v0
	v_mov_b32_e32 v83, v0
	v_mov_b32_e32 v84, v0
	v_mov_b32_e32 v85, v0
	v_mov_b32_e32 v86, v0
	v_mov_b32_e32 v87, v0
	v_mov_b32_e32 v88, v0
	v_mov_b32_e32 v89, v0
	v_mov_b32_e32 v90, v0
	v_mov_b32_e32 v91, v0
	v_mov_b32_e32 v92, v0
	v_mov_b32_e32 v93, v0
	v_mov_b32_e32 v94, v0
	v_mov_b32_e32 v95, v0
	v_mov_b32_e32 v96, v0
	v_mov_b32_e32 v97, v0
	v_mov_b32_e32 v98, v0
	v_mov_b32_e32 v99, v0
	v_mov_b32_e32 v100, v0
	v_mov_b32_e32 v101, v0
	v_mov_b32_e32 v102, v0
	v_mov_b32_e32 v103, v0
	v_mov_b32_e32 v104, v0
	v_mov_b32_e32 v105, v0
	v_mov_b32_e32 v106, v0
	v_mov_b32_e32 v107, v0
	v_mov_b32_e32 v108, v0
	v_mov_b32_e32 v109, v0
	v_mov_b32_e32 v110, v0
	v_mov_b32_e32 v111, v0
	v_mov_b32_e32 v112, v0
	v_mov_b32_e32 v113, v0
	v_mov_b32_e32 v114, v0
	v_mov_b32_e32 v115, v0
	v_mov_b32_e32 v116, v0
	v_mov_b32_e32 v117, v0
	v_mov_b32_e32 v118, v0
	v_mov_b32_e32 v119, v0
	v_mov_b32_e32 v120, v0
	v_mov_b32_e32 v121, v0
	v_mov_b32_e32 v122, v0
	v_mov_b32_e32 v123, v0
	v_mov_b32_e32 v124, v0
	v_mov_b32_e32 v125, v0
	v_mov_b32_e32 v126, v0
	v_mov_b32_e32 v127, v0
	v_mov_b32_e32 v128, v0
	v_mov_b32_e32 v129, v0
	v_readfirstlane_b32 s99, v152
	s_lshl_b32 s99, s99, 1
	.p2align 6

; template <bool VT>
; DI int gemm_kloop(const bf16_t* Ag, size_t lda, const bf16_t* Bg, size_t ldb, int nk, bf16_t* ring, f32x16 (&acc)[4][2], int tid, int wm, int wn,
;                   int r, int h, int st0, bool pre, const bf16_t* AgN, const bf16_t* BgN) {
;   const int wid = tid >> 6, lane = tid & 63;
;   const unsigned base = (unsigned)(unsigned long long)ring;
;   const int q = (r >> 2) & 3;
;   const unsigned rA = base + (unsigned)(wm * 128 + r) * 64u, rB = base + (unsigned)STG_A * 2u + (unsigned)(wn * 64 + r) * 64u;
;   const unsigned oA0 = rA + (unsigned)((h ^ q) & 3) * 16u, oA1 = rA + (unsigned)(((2 + h) ^ q) & 3) * 16u;
;   const unsigned oB0 = rB + (unsigned)((h ^ q) & 3) * 16u, oB1 = rB + (unsigned)(((2 + h) ^ q) & 3) * 16u;
;     ...
;   f32x16 acc[4][2];
; #pragma unroll
;   for (int a = 0; a < 4; ++a)
; #pragma unroll
;     for (int b = 0; b < 2; ++b)
; #pragma unroll
;       for (int i = 0; i < 16; ++i) acc[a][b][i] = 0.f;
;   const bool vt = epi.vtype(n0 + wn * 64);
;   int st_last = 0;
;   if (pm == 2) K >>= 1;
;   if (DEEP) {
;     const bf16_t* AgN = tmN >= 0 ? A + (size_t)(tmN << 8) * lda : nullptr;
;     const bf16_t* BgN = Bt + (size_t)(tnN << 7) * ldb;
;     if (vt) st_last = gemm_kloop<true>(Ag, lda, Bg, ldb, K >> 5, sA, acc, tid, wm, wn, r, h, st0, pre, AgN, BgN);
;     else st_last = gemm_kloop<false>(Ag, lda, Bg, ldb, K >> 5, sA, acc, tid, wm, wn, r, h, st0, pre, AgN, BgN);
.LBB0_1261:
	v_and_b32_e32 v154, 31, v152
	v_bfe_u32 v155, v152, 5, 1
	v_and_b32_e32 v156, 1, v153
	v_lshrrev_b32_e32 v0, 2, v152
	v_bfe_u32 v1, v152, 2, 2
	v_lshlrev_b32_e32 v2, 6, v152
	v_lshlrev_b32_e32 v3, 6, v154
	v_lshlrev_b32_e32 v4, 12, v156
	v_bitop3_b32 v0, v0, v155, 3 bitop3:0x6c
	v_bitop3_b32 v1, v155, v1, 2 bitop3:0x36
	s_and_b32 s33, s23, 7
	s_mov_b64 s[8:9], s[14:15]
	v_and_or_b32 v2, v2, s93, v3
	v_or3_b32 v3, v3, v4, s94
	v_lshlrev_b32_e32 v0, 4, v0
	v_lshlrev_b32_e32 v1, 4, v1
	v_lshlrev_b64 v[138:139], 1, v[32:33]
	s_add_u32 s14, s21, s30
	v_or_b32_e32 v157, v0, v2
	v_or_b32_e32 v158, v1, v2
	v_or_b32_e32 v159, v3, v0
	v_or_b32_e32 v160, v1, v3
	v_lshl_add_u64 v[0:1], v[132:133], 1, v[138:139]
	s_addc_u32 s15, s22, s31
	v_lshl_add_u64 v[2:3], v[130:131], 1, v[138:139]
	s_add_i32 s28, s28, s33
	v_lshl_add_u64 v[140:141], s[14:15], 0, v[0:1]
	v_lshl_add_u64 v[142:143], s[14:15], 0, v[2:3]
	s_lshl_b32 s14, s28, 11
	s_or_b32 s28, s14, s29
	v_lshlrev_b64 v[4:5], 1, v[136:137]
	v_mad_i64_i32 v[4:5], s[14:15], s28, v211, v[4:5]
	v_lshl_add_u64 v[4:5], v[4:5], 0, v[138:139]
	v_lshl_add_u64 v[144:145], s[4:5], 0, v[4:5]
	v_lshlrev_b64 v[4:5], 1, v[134:135]
	v_mad_i64_i32 v[0:1], s[14:15], s28, v211, v[0:1]
	v_mad_i64_i32 v[4:5], s[14:15], s28, v211, v[4:5]
	v_lshl_add_u64 v[148:149], s[4:5], 0, v[0:1]
	v_mad_i64_i32 v[0:1], s[14:15], s28, v211, v[2:3]
	v_lshl_add_u64 v[4:5], v[4:5], 0, v[138:139]
	v_lshl_add_u64 v[150:151], s[4:5], 0, v[0:1]
	v_mov_b32_e32 v0, 0
	v_lshlrev_b32_e32 v164, 10, v8
	v_lshlrev_b32_e32 v163, 10, v9
	v_lshl_add_u64 v[146:147], s[4:5], 0, v[4:5]
	s_mov_b64 s[14:15], 0
	v_mov_b32_e32 v1, v0
	v_mov_b32_e32 v2, v0
	v_mov_b32_e32 v3, v0
	v_mov_b32_e32 v4, v0
	v_mov_b32_e32 v5, v0
	v_mov_b32_e32 v6, v0
	v_mov_b32_e32 v7, v0
	v_mov_b32_e32 v8, v0
	v_mov_b32_e32 v9, v0
	v_mov_b32_e32 v10, v0
	v_mov_b32_e32 v11, v0
	v_mov_b32_e32 v12, v0
	v_mov_b32_e32 v13, v0
	v_mov_b32_e32 v14, v0
	v_mov_b32_e32 v15, v0
	v_mov_b32_e32 v16, v0
	v_mov_b32_e32 v17, v0
	v_mov_b32_e32 v18, v0
	v_mov_b32_e32 v19, v0
	v_mov_b32_e32 v20, v0
	v_mov_b32_e32 v21, v0
	v_mov_b32_e32 v22, v0
	v_mov_b32_e32 v23, v0
	v_mov_b32_e32 v24, v0
	v_mov_b32_e32 v25, v0
	v_mov_b32_e32 v26, v0
	v_mov_b32_e32 v27, v0
	v_mov_b32_e32 v28, v0
	v_mov_b32_e32 v29, v0
	v_mov_b32_e32 v30, v0
	v_mov_b32_e32 v31, v0
	v_mov_b32_e32 v34, v0
	v_mov_b32_e32 v35, v0
	v_mov_b32_e32 v36, v0
	v_mov_b32_e32 v37, v0
	v_mov_b32_e32 v38, v0
	v_mov_b32_e32 v39, v0
	v_mov_b32_e32 v40, v0
	v_mov_b32_e32 v41, v0
	v_mov_b32_e32 v42, v0
	v_mov_b32_e32 v43, v0
	v_mov_b32_e32 v44, v0
	v_mov_b32_e32 v45, v0
	v_mov_b32_e32 v46, v0
	v_mov_b32_e32 v47, v0
	v_mov_b32_e32 v48, v0
	v_mov_b32_e32 v49, v0
	v_mov_b32_e32 v50, v0
	v_mov_b32_e32 v51, v0
	v_mov_b32_e32 v52, v0
	v_mov_b32_e32 v53, v0
	v_mov_b32_e32 v54, v0
	v_mov_b32_e32 v55, v0
	v_mov_b32_e32 v56, v0
	v_mov_b32_e32 v57, v0
	v_mov_b32_e32 v58, v0
	v_mov_b32_e32 v59, v0
	v_mov_b32_e32 v60, v0
	v_mov_b32_e32 v61, v0
	v_mov_b32_e32 v62, v0
	v_mov_b32_e32 v63, v0
	v_mov_b32_e32 v64, v0
	v_mov_b32_e32 v65, v0
	v_mov_b32_e32 v66, v0
	v_mov_b32_e32 v67, v0
	v_mov_b32_e32 v68, v0
	v_mov_b32_e32 v69, v0
	v_mov_b32_e32 v70, v0
	v_mov_b32_e32 v71, v0
	v_mov_b32_e32 v72, v0
	v_mov_b32_e32 v73, v0
	v_mov_b32_e32 v74, v0
	v_mov_b32_e32 v75, v0
	v_mov_b32_e32 v76, v0
	v_mov_b32_e32 v77, v0
	v_mov_b32_e32 v78, v0
	v_mov_b32_e32 v79, v0
	v_mov_b32_e32 v80, v0
	v_mov_b32_e32 v81, v0
	v_mov_b32_e32 v82, v0
	v_mov_b32_e32 v83, v0
	v_mov_b32_e32 v84, v0
	v_mov_b32_e32 v85, v0
	v_mov_b32_e32 v86, v0
	v_mov_b32_e32 v87, v0
	v_mov_b32_e32 v88, v0
	v_mov_b32_e32 v89, v0
	v_mov_b32_e32 v90, v0
	v_mov_b32_e32 v91, v0
	v_mov_b32_e32 v92, v0
	v_mov_b32_e32 v93, v0
	v_mov_b32_e32 v94, v0
	v_mov_b32_e32 v95, v0
	v_mov_b32_e32 v96, v0
	v_mov_b32_e32 v97, v0
	v_mov_b32_e32 v98, v0
	v_mov_b32_e32 v99, v0
	v_mov_b32_e32 v100, v0
	v_mov_b32_e32 v101, v0
	v_mov_b32_e32 v102, v0
	v_mov_b32_e32 v103, v0
	v_mov_b32_e32 v104, v0
	v_mov_b32_e32 v105, v0
	v_mov_b32_e32 v106, v0
	v_mov_b32_e32 v107, v0
	v_mov_b32_e32 v108, v0
	v_mov_b32_e32 v109, v0
	v_mov_b32_e32 v110, v0
	v_mov_b32_e32 v111, v0
	v_mov_b32_e32 v112, v0
	v_mov_b32_e32 v113, v0
	v_mov_b32_e32 v114, v0
	v_mov_b32_e32 v115, v0
	v_mov_b32_e32 v116, v0
	v_mov_b32_e32 v117, v0
	v_mov_b32_e32 v118, v0
	v_mov_b32_e32 v119, v0
	v_mov_b32_e32 v120, v0
	v_mov_b32_e32 v121, v0
	v_mov_b32_e32 v122, v0
	v_mov_b32_e32 v123, v0
	v_mov_b32_e32 v124, v0
	v_mov_b32_e32 v125, v0
	v_mov_b32_e32 v126, v0
	v_mov_b32_e32 v127, v0
	v_mov_b32_e32 v128, v0
	v_mov_b32_e32 v129, v0
	v_readfirstlane_b32 s99, v162
	s_lshl_b32 s99, s99, 1
	.p2align 6

; DI int otid() { int t = threadIdx.x; asm volatile("" : "+v"(t)); return t; }
;   const int tid = otid();
;   const int lane = tid & 63, wid = tid >> 6, r = lane & 31, h = lane >> 5, wm = wid >> 1, wn = wid & 1;
;   bf16_t* sA = (bf16_t*)smem;
;   bf16_t* sB = sA;
;   float* sR = (float*)(smem + 73728);
;   const int m0 = tm << 8, n0 = tn << 7;
;   const bf16_t* Ag = A + (size_t)m0 * lda;
;   const bf16_t* Bg = Bt + (size_t)n0 * ldb;
;   if (ssq) {
;     const f32x4* sp = (const f32x4*)(ssq + (size_t)(m0 + tid) * 16);
;     const f32x4 a = sp[0], b = sp[1], c = sp[2], d = sp[3];
;     const float tot = ((a.x + a.y) + (a.z + a.w)) + ((b.x + b.y) + (b.z + b.w)) + ((c.x + c.y) + (c.z + c.w)) + ((d.x + d.y) + (d.z + d.w));
;     sR[tid] = rsqrtf(tot * (1.f / DM) + 1e-6f);
;   }
;   __syncthreads();
;     ...
;   for (int t = blockIdx.x; t < ntiles; t += gridDim.x) {
;     const int xcd = t & 7, j = t >> 3;
;     const int grp = j / (8 * nN), jj = j % (8 * nN);
;     const int tm = xcd * band + grp * 8 + (jj & 7), tn = jj >> 3;
.LBB0_1314:
	s_ashr_i32 s9, s18, 31
	s_ashr_i32 s8, s18, 3
	s_lshr_b32 s9, s9, 26
	s_add_i32 s9, s8, s9
	s_ashr_i32 s27, s9, 6
	s_andn2_b32 s9, s9, 63
	s_sub_i32 s8, s8, s9
	s_and_b32 s9, s18, 7
	s_add_i32 s9, s27, s9
	v_mov_b32_e32 v143, v242
	s_lshl_b32 s20, s8, 8
	s_lshl_b32 s8, s8, 4
	s_lshl_b32 s9, s9, 11
	v_ashrrev_i32_e32 v145, 6, v143
	s_and_b32 s28, s20, 0x700
	s_and_b32 s21, s8, 0xffffff80
	v_bfe_u32 v144, v143, 5, 1
	s_or_b32 s20, s9, s28
	s_mul_i32 s8, s21, 0xb40
	s_waitcnt vmcnt(0)
	v_and_b32_e32 v146, 31, v143
	v_and_b32_e32 v151, 1, v145
	v_lshrrev_b32_e32 v0, 2, v143
	s_and_b32 s26, s17, 7
	s_ashr_i32 s9, s8, 31
	s_mul_i32 s22, s20, 0x1680
	v_lshlrev_b32_e32 v2, 6, v143
	v_lshlrev_b32_e32 v3, 6, v146
	v_lshlrev_b32_e32 v4, 12, v151
	v_bitop3_b32 v0, v0, v144, 3 bitop3:0x6c
	s_mul_hi_i32 s23, s20, 0x1680
	s_add_u32 s22, s10, s22
	v_bfe_u32 v1, v143, 2, 2
	v_and_or_b32 v2, v2, s93, v3
	v_or3_b32 v3, v3, v4, s94
	v_lshlrev_b32_e32 v0, 4, v0
	v_bfe_u32 v142, v143, 4, 2
	s_addc_u32 s23, s11, s23
	s_lshl_b64 s[8:9], s[8:9], 1
	v_or_b32_e32 v147, v0, v2
	v_bitop3_b32 v1, v144, v1, 2 bitop3:0x36
	v_or_b32_e32 v149, v3, v0
	v_bitop3_b32 v0, v142, v143, 3 bitop3:0x78
	s_add_u32 s24, s12, s8
	v_lshlrev_b32_e32 v1, 4, v1
	s_mul_i32 s29, s19, 0x3000
	v_bfe_u32 v8, v143, 2, 4
	v_lshlrev_b32_e32 v32, 4, v0
	s_addc_u32 s25, s13, s9
	v_or_b32_e32 v148, v1, v2
	v_or_b32_e32 v150, v1, v3
	s_lshl_b32 s30, s29, 1
	v_lshl_add_u64 v[0:1], s[22:23], 0, v[32:33]
	v_lshl_or_b32 v12, v145, 4, v8
	s_movk_i32 s31, 0x1680
	v_lshlrev_b32_e32 v13, 10, v145
	v_mad_i64_i32 v[2:3], s[22:23], v12, s31, v[0:1]
	v_add_u32_e32 v14, s30, v13
	v_add_u32_e32 v6, 4, v145
	v_readfirstlane_b32 s22, v14
	v_lshl_or_b32 v15, v6, 4, v8
	v_lshlrev_b32_e32 v16, 10, v6
	s_mov_b32 m0, s22
	v_mad_i64_i32 v[4:5], s[22:23], v15, s31, v[0:1]
	v_add_u32_e32 v17, s30, v16
	v_add_u32_e32 v9, 8, v145
	v_lshlrev_b32_e32 v153, 9, v6
	v_readfirstlane_b32 s22, v17
	v_lshl_or_b32 v6, v9, 4, v8
	v_lshlrev_b32_e32 v154, 10, v9
	s_waitcnt lgkmcnt(0)
	s_barrier
; DI void dma_issue(const bf16_t* Ag, size_t lda, const bf16_t* Bg, size_t ldb, int kt, bf16_t* stage, int wid, int lane) {
;   const int rl = lane >> 2, c = (lane & 3) ^ ((lane >> 4) & 3);
; #pragma unroll
;   for (int i = 0; i < 4; ++i) {
;     const int j = wid + 4 * i;
;     __builtin_amdgcn_global_load_lds((const unsigned*)(Ag + (size_t)(16 * j + rl) * lda + kt * 32 + c * 8), (unsigned*)(stage + j * 512), 16, 0, 0);
;   }
; #pragma unroll
;   for (int i = 0; i < 2; ++i) {
;     const int j = wid + 4 * i;
;     __builtin_amdgcn_global_load_lds((const unsigned*)(Bg + (size_t)(16 * j + rl) * ldb + kt * 32 + c * 8), (unsigned*)(stage + STG_A + j * 512), 16, 0, 0);
;   }
; }
;     ...
;   f32x16 acc[4][2];
; #pragma unroll
;   for (int a = 0; a < 4; ++a)
; #pragma unroll
;     for (int b = 0; b < 2; ++b)
; #pragma unroll
;       for (int i = 0; i < 16; ++i) acc[a][b][i] = 0.f;
	global_load_lds_dwordx4 v[2:3], off
	s_mov_b32 m0, s22
	v_mad_i64_i32 v[6:7], s[22:23], v6, s31, v[0:1]
	v_add_u32_e32 v9, s30, v154
	global_load_lds_dwordx4 v[4:5], off
	v_readfirstlane_b32 s22, v9
	v_add_u32_e32 v9, 12, v145
	v_lshl_or_b32 v8, v9, 4, v8
	v_lshlrev_b32_e32 v155, 10, v9
	s_mov_b32 m0, s22
	v_mad_i64_i32 v[0:1], s[22:23], v8, s31, v[0:1]
	v_add_u32_e32 v8, s30, v155
	global_load_lds_dwordx4 v[6:7], off
	v_readfirstlane_b32 s22, v8
	v_lshl_add_u64 v[8:9], s[24:25], 0, v[32:33]
	s_mov_b32 m0, s22
	v_mad_i64_i32 v[10:11], s[22:23], v12, s31, v[8:9]
	v_add_u32_e32 v14, 0x4000, v14
	global_load_lds_dwordx4 v[0:1], off
	v_readfirstlane_b32 s22, v14
	s_mov_b32 m0, s22
	v_mad_i64_i32 v[8:9], s[22:23], v15, s31, v[8:9]
	v_add_u32_e32 v14, 0x4000, v17
	s_addk_i32 s29, 0x3000
	v_readfirstlane_b32 s22, v14
	s_cmp_lg_u32 s19, 2
	global_load_lds_dwordx4 v[10:11], off
	s_mov_b32 m0, s22
	s_cselect_b32 s22, s29, 0
	s_lshl_b32 s22, s22, 1
	v_add_u32_e32 v13, s22, v13
	global_load_lds_dwordx4 v[8:9], off
	v_readfirstlane_b32 s23, v13
	v_lshl_add_u64 v[2:3], v[2:3], 0, 64
	s_mov_b32 m0, s23
	v_lshl_add_u64 v[0:1], v[0:1], 0, 64
	global_load_lds_dwordx4 v[2:3], off
	v_lshl_add_u64 v[2:3], v[4:5], 0, 64
	v_add_u32_e32 v4, s22, v16
	v_add_u32_e32 v5, s22, v154
	v_readfirstlane_b32 s23, v4
	s_mov_b32 m0, s23
	v_readfirstlane_b32 s23, v5
	global_load_lds_dwordx4 v[2:3], off
	v_lshl_add_u64 v[2:3], v[6:7], 0, 64
	s_mov_b32 m0, s23
	s_add_u32 s8, s15, s8
	global_load_lds_dwordx4 v[2:3], off
	v_add_u32_e32 v2, s22, v155
	s_addc_u32 s9, s16, s9
	v_readfirstlane_b32 s22, v2
	v_add_u32_e32 v2, 0x4000, v13
	s_mov_b32 m0, s22
	v_readfirstlane_b32 s22, v2
	v_add_u32_e32 v2, 0x4000, v4
	global_load_lds_dwordx4 v[0:1], off
	v_lshl_add_u64 v[0:1], v[10:11], 0, 64
	s_mov_b32 m0, s22
	v_readfirstlane_b32 s22, v2
	global_load_lds_dwordx4 v[0:1], off
	v_lshl_add_u64 v[0:1], v[8:9], 0, 64
	s_mov_b32 m0, s22
	v_mad_i64_i32 v[2:3], s[22:23], v12, s31, 0
	global_load_lds_dwordx4 v[0:1], off
	v_add_u32_e32 v0, 64, v12
	v_mad_i64_i32 v[0:1], s[22:23], v0, s31, 0
	v_or_b32_e32 v0, v0, v32
	v_or_b32_e32 v2, v2, v32
	s_add_i32 s27, s27, s26
	v_lshl_add_u64 v[130:131], s[8:9], 0, v[0:1]
	v_lshl_add_u64 v[132:133], s[8:9], 0, v[2:3]
	s_lshl_b32 s8, s27, 11
	s_or_b32 s22, s8, s28
	s_mul_hi_i32 s9, s22, 0x1680
	s_mul_i32 s8, s22, 0x1680
	v_add_u32_e32 v6, 0xc0, v12
	v_mov_b64_e32 v[4:5], s[8:9]
	v_mad_i64_i32 v[6:7], s[8:9], v6, s31, v[4:5]
	v_or_b32_e32 v6, v6, v32
	v_lshl_add_u64 v[134:135], s[6:7], 0, v[6:7]
	v_add_u32_e32 v6, 0x80, v12
	v_mad_i64_i32 v[4:5], s[8:9], v6, s31, v[4:5]
	v_or_b32_e32 v4, v4, v32
	v_lshl_add_u64 v[136:137], s[6:7], 0, v[4:5]
	v_mov_b32_e32 v4, 0x1680
	v_mad_i64_i32 v[0:1], s[8:9], s22, v4, v[0:1]
	v_lshl_add_u64 v[138:139], s[6:7], 0, v[0:1]
	v_mad_i64_i32 v[0:1], s[8:9], s22, v4, v[2:3]
	v_lshl_add_u64 v[140:141], s[6:7], 0, v[0:1]
	v_mov_b32_e32 v0, 0
	v_lshlrev_b32_e32 v152, 9, v145
	s_mov_b64 s[8:9], 0
	v_mov_b32_e32 v1, v0
	v_mov_b32_e32 v2, v0
	v_mov_b32_e32 v3, v0
	v_mov_b32_e32 v4, v0
	v_mov_b32_e32 v5, v0
	v_mov_b32_e32 v6, v0
	v_mov_b32_e32 v7, v0
	v_mov_b32_e32 v8, v0
	v_mov_b32_e32 v9, v0
	v_mov_b32_e32 v10, v0
	v_mov_b32_e32 v11, v0
	v_mov_b32_e32 v12, v0
	v_mov_b32_e32 v13, v0
	v_mov_b32_e32 v14, v0
	v_mov_b32_e32 v15, v0
	v_mov_b32_e32 v16, v0
	v_mov_b32_e32 v17, v0
	v_mov_b32_e32 v18, v0
	v_mov_b32_e32 v19, v0
	v_mov_b32_e32 v20, v0
	v_mov_b32_e32 v21, v0
	v_mov_b32_e32 v22, v0
	v_mov_b32_e32 v23, v0
	v_mov_b32_e32 v24, v0
	v_mov_b32_e32 v25, v0
	v_mov_b32_e32 v26, v0
	v_mov_b32_e32 v27, v0
	v_mov_b32_e32 v28, v0
	v_mov_b32_e32 v29, v0
	v_mov_b32_e32 v30, v0
	v_mov_b32_e32 v31, v0
	v_mov_b32_e32 v34, v0
	v_mov_b32_e32 v35, v0
	v_mov_b32_e32 v36, v0
	v_mov_b32_e32 v37, v0
	v_mov_b32_e32 v38, v0
	v_mov_b32_e32 v39, v0
	v_mov_b32_e32 v40, v0
	v_mov_b32_e32 v41, v0
	v_mov_b32_e32 v42, v0
	v_mov_b32_e32 v43, v0
	v_mov_b32_e32 v44, v0
	v_mov_b32_e32 v45, v0
	v_mov_b32_e32 v46, v0
	v_mov_b32_e32 v47, v0
	v_mov_b32_e32 v48, v0
	v_mov_b32_e32 v49, v0
	v_mov_b32_e32 v50, v0
	v_mov_b32_e32 v51, v0
	v_mov_b32_e32 v52, v0
	v_mov_b32_e32 v53, v0
	v_mov_b32_e32 v54, v0
	v_mov_b32_e32 v55, v0
	v_mov_b32_e32 v56, v0
	v_mov_b32_e32 v57, v0
	v_mov_b32_e32 v58, v0
	v_mov_b32_e32 v59, v0
	v_mov_b32_e32 v60, v0
	v_mov_b32_e32 v61, v0
	v_mov_b32_e32 v62, v0
	v_mov_b32_e32 v63, v0
	v_mov_b32_e32 v64, v0
	v_mov_b32_e32 v65, v0
	v_mov_b32_e32 v66, v0
	v_mov_b32_e32 v67, v0
	v_mov_b32_e32 v68, v0
	v_mov_b32_e32 v69, v0
	v_mov_b32_e32 v70, v0
	v_mov_b32_e32 v71, v0
	v_mov_b32_e32 v72, v0
	v_mov_b32_e32 v73, v0
	v_mov_b32_e32 v74, v0
	v_mov_b32_e32 v75, v0
	v_mov_b32_e32 v76, v0
	v_mov_b32_e32 v77, v0
	v_mov_b32_e32 v78, v0
	v_mov_b32_e32 v79, v0
	v_mov_b32_e32 v80, v0
	v_mov_b32_e32 v81, v0
	v_mov_b32_e32 v82, v0
	v_mov_b32_e32 v83, v0
	v_mov_b32_e32 v84, v0
	v_mov_b32_e32 v85, v0
	v_mov_b32_e32 v86, v0
	v_mov_b32_e32 v87, v0
	v_mov_b32_e32 v88, v0
	v_mov_b32_e32 v89, v0
	v_mov_b32_e32 v90, v0
	v_mov_b32_e32 v91, v0
	v_mov_b32_e32 v92, v0
	v_mov_b32_e32 v93, v0
	v_mov_b32_e32 v94, v0
	v_mov_b32_e32 v95, v0
	v_mov_b32_e32 v96, v0
	v_mov_b32_e32 v97, v0
	v_mov_b32_e32 v98, v0
	v_mov_b32_e32 v99, v0
	v_mov_b32_e32 v100, v0
	v_mov_b32_e32 v101, v0
	v_mov_b32_e32 v102, v0
	v_mov_b32_e32 v103, v0
	v_mov_b32_e32 v104, v0
	v_mov_b32_e32 v105, v0
	v_mov_b32_e32 v106, v0
	v_mov_b32_e32 v107, v0
	v_mov_b32_e32 v108, v0
	v_mov_b32_e32 v109, v0
	v_mov_b32_e32 v110, v0
	v_mov_b32_e32 v111, v0
	v_mov_b32_e32 v112, v0
	v_mov_b32_e32 v113, v0
	v_mov_b32_e32 v114, v0
	v_mov_b32_e32 v115, v0
	v_mov_b32_e32 v116, v0
	v_mov_b32_e32 v117, v0
	v_mov_b32_e32 v118, v0
	v_mov_b32_e32 v119, v0
	v_mov_b32_e32 v120, v0
	v_mov_b32_e32 v121, v0
	v_mov_b32_e32 v122, v0
	v_mov_b32_e32 v123, v0
	v_mov_b32_e32 v124, v0
	v_mov_b32_e32 v125, v0
	v_mov_b32_e32 v126, v0
	v_mov_b32_e32 v127, v0
	v_mov_b32_e32 v128, v0
	v_mov_b32_e32 v129, v0
	v_readfirstlane_b32 s99, v152
	s_lshl_b32 s99, s99, 1
	.p2align 6
